# v8 + w_gu weight conversion moved from the GU tail workers to the attention-phase idle WGs
# speedup vs baseline: 1.0087x; 1.0087x over previous
; #define LAS __attribute__((address_space(3)))
; #define LAS __attribute__((address_space(3)))
; __global__ void __launch_bounds__(NWAVES * 64, 2) hymba_fwd(Args args) {
;     ...
;                 if (l + 1 < DEPTH && blockIdx.x >= 48) {
;                     int ln = lane, tn = tid; asm volatile("" : "+v"(ln), "+v"(tn));
;                     const int wk = ((int)blockIdx.x - 48) * NWAVES + wave, nwk = (G - 48) * NWAVES;
;                     convert_layer_weights(args, ws, (LAS float*)(lds + wave * 16384), l + 1, wk, nwk, ln, 12);
;                     convert_layer_caches(args, ws, (LAS float*)(lds + wave * 16384), l + 1, wk, nwk, ((int)blockIdx.x - 48) * (NWAVES * 64) + tn, (G - 48) * NWAVES * 64, ln);
.LBB0_46:
	v_readlane_b32 s98, v251, 0
	s_nop 0
	s_cmp_ge_u32 s98, 0xb0
	s_cbranch_scc1 .LBB0_204
	s_cmp_gt_i32 s54, 15
	v_readlane_b32 s2, v255, 5
	s_cselect_b64 s[0:1], -1, 0
	v_readlane_b32 s3, v255, 6
	s_or_b64 s[0:1], s[2:3], s[0:1]
	s_and_b64 vcc, exec, s[0:1]
	s_cbranch_vccnz .LBB0_204
	v_readlane_b32 s0, v255, 19
	v_readlane_b32 s1, v255, 20
	s_add_i32 s4, s0, 1
	v_readlane_b32 s0, v251, 9
	v_and_b32_e32 v55, 63, v216
	v_mov_b32_e32 v1, v216
	v_readlane_b32 s1, v251, 10
	s_andn2_b64 vcc, exec, s[0:1]
	v_ashrrev_i32_e32 v18, 5, v55
	v_ashrrev_i32_e32 v19, 3, v55
	v_lshlrev_b32_e32 v0, 3, v55
	s_movk_i32 s0, 0x84
	v_mul_lo_u32 v20, v18, s0
	v_add_u32_e32 v21, 2, v18
	v_add_u32_e32 v22, 4, v18
	v_add_u32_e32 v23, 6, v18
	v_add_u32_e32 v24, 8, v18
	v_add_u32_e32 v25, 10, v18
	v_add_u32_e32 v26, 12, v18
	v_add_u32_e32 v27, 14, v18
	v_add_u32_e32 v28, 16, v18
	v_add_u32_e32 v29, 18, v18
	v_add_u32_e32 v30, 20, v18
	v_add_u32_e32 v31, 22, v18
	v_add_u32_e32 v32, 24, v18
	v_add_u32_e32 v33, 26, v18
	v_add_u32_e32 v34, 28, v18
	v_add_u32_e32 v35, 30, v18
	v_add_u32_e32 v36, 32, v18
	v_add_u32_e32 v37, 34, v18
	v_add_u32_e32 v38, 36, v18
	v_add_u32_e32 v39, 38, v18
	v_add_u32_e32 v40, 40, v18
	v_add_u32_e32 v41, 42, v18
	v_add_u32_e32 v42, 44, v18
	v_add_u32_e32 v43, 46, v18
	v_add_u32_e32 v44, 48, v18
	v_add_u32_e32 v45, 50, v18
	v_add_u32_e32 v46, 52, v18
	v_add_u32_e32 v47, 54, v18
	v_add_u32_e32 v48, 56, v18
	v_add_u32_e32 v49, 58, v18
	v_add_u32_e32 v50, 60, v18
	v_add_u32_e32 v51, 62, v18
	v_and_b32_e32 v0, 56, v0
	v_lshlrev_b32_e32 v56, 2, v19
	v_add_u32_e32 v52, 8, v19
	v_add_u32_e32 v53, 16, v19
	v_add_u32_e32 v54, 24, v19
	v_readlane_b32 s6, v251, 14
	s_cbranch_vccnz .LBB0_191
	s_lshl_b32 s100, s4, 8
	s_or_b32 s100, s100, 0x5300008
	s_mov_b32 s101, 1
	s_branch .Lcvt_entry

; #define LAS __attribute__((address_space(3)))
; #define LAS __attribute__((address_space(3)))
; __global__ void __launch_bounds__(NWAVES * 64, 2) hymba_fwd(Args args) {
;     ...
;                 if (l + 1 < DEPTH && blockIdx.x >= 64) {
;                     int ln = lane; asm volatile("" : "+v"(ln));
;                     convert_layer_weights(args, ws, (LAS float*)(lds + wave * 16384), l + 1, ((int)blockIdx.x - 64) * NWAVES + wave, (G - 64) * NWAVES, ln, 3);
;                     if (l == 0) { int tn = tid; asm volatile("" : "+v"(tn)); copy_window_outputs(args, ((int)blockIdx.x - 64) * (NWAVES * 64) + tn, (G - 64) * NWAVES * 64); }
.LBB0_294:
	v_readlane_b32 s2, v251, 31
	s_cmp_gt_i32 s54, 15
	v_readlane_b32 s3, v251, 32
	s_cselect_b64 s[0:1], -1, 0
	s_xor_b64 s[2:3], s[2:3], -1
	s_or_b64 s[0:1], s[2:3], s[0:1]
	v_readlane_b32 s94, v255, 12
	s_and_b64 vcc, exec, s[0:1]
	v_readlane_b32 s92, v255, 11
	v_readlane_b32 s95, v255, 13
	v_readlane_b32 s6, v251, 40
	v_readlane_b32 s93, v255, 16
	v_readlane_b32 s18, v254, 30
	v_readlane_b32 s19, v254, 35
	s_movk_i32 s29, 0x5800
	s_cbranch_vccnz .LBB0_440
	v_readlane_b32 s0, v251, 33
	v_readlane_b32 s1, v251, 34
	v_and_b32_e32 v0, 63, v216
	s_andn2_b64 vcc, exec, s[0:1]
	s_nop 0
	v_readlane_b32 s100, v255, 19
	s_add_i32 s100, s100, 1
	s_lshl_b32 s100, s100, 8
	s_or_b32 s100, s100, 0x400007
	s_mov_b32 s101, 3
	s_branch .Lcvt_entry
